# v23 plus: per-item redo flag handled with ds_write/ds_read instead of flat ops, so the item-end wait no longer drains the 32 output stores; MLA item-start vmcnt(0) removed
# speedup vs baseline: 1.0094x; 1.0094x over previous
; template <int DQ, bool WIN, int LDQ, int LDK> ...
;     ...
;     volatile int* redo_flag = (volatile int*)(lds + 2 * SHM_V + 2 * SHM_K + 8 * 64 * 4);
;     if (tid == 0) *redo_flag = 0;
; __device__ __forceinline__ void phase_attn0(const Params& p, char* lds) {
;     ...
;     for (int it = blockIdx.x; it < 4096; it += gridDim.x) {
;         const int win = it >> 11, r = it & 2047, b = r >> 8, hq = (r >> 5) & 7, qb = r & 31, kvh = hq >> 2;
;         const size_t tok0 = (size_t)b * SEQ; const int q0 = qb * 256;
;         if (!win) {
;             if (attn_body<64, false, 1536, 1536>(proj + (tok0 + q0) * 1536 + hq * 64, proj + tok0 * 1536 + 512 + kvh * 64, nullptr, proj + tok0 * 1536 + 640 + kvh * 64,
.LBB0_412:
	s_lshr_b32 s0, s66, 5
	s_bfe_u32 s37, s0, 0x10002
	s_lshl_b32 s0, s66, 5
	s_and_b32 s65, s0, 0xe000
	s_lshl_b32 s0, s66, 8
	s_bfe_u32 s67, s75, 0x3000d
	s_and_b32 s33, s66, 0x80
	s_bfe_u32 s64, s66, 0x30005
	s_and_b32 s63, s0, 0x1f00
	s_mul_i32 s67, s67, 0x1800000
	s_cmpk_gt_u32 s66, 0x7ff
	s_mul_i32 s62, s65, 0xc00
	s_cbranch_scc0 .LBB0_424
	s_lshl_b32 s0, s64, 2
	v_readlane_b32 s40, v252, 14
	v_mov_b32_e32 v1, s0
	v_readlane_b32 s48, v252, 22
	v_readlane_b32 s49, v252, 23
	s_add_u32 s34, s48, s0
	v_mov_b32_e32 v42, v181
	s_addc_u32 s35, s49, 0
	v_readlane_b32 s41, v252, 15
	v_readlane_b32 s42, v252, 16
	global_load_dword v158, v1, s[48:49]
	v_readlane_b32 s43, v252, 17
	v_readfirstlane_b32 s9, v42
	v_cmp_eq_u32_e32 vcc, 0, v42
	v_readlane_b32 s44, v252, 18
	v_readlane_b32 s45, v252, 19
	v_readlane_b32 s46, v252, 20
	v_readlane_b32 s47, v252, 21
	v_readlane_b32 s50, v252, 24
	v_readlane_b32 s51, v252, 25
	v_readlane_b32 s52, v252, 26
	v_readlane_b32 s53, v252, 27
	v_readlane_b32 s54, v252, 28
	v_readlane_b32 s55, v252, 29
	s_and_saveexec_b64 s[0:1], vcc
	s_cbranch_execz .LBB0_415
	s_mov_b64 s[4:5], src_shared_base
	s_cmp_lg_u32 s97, -1
	s_cselect_b32 s4, s97, 0
	s_cselect_b32 s5, s5, 0
	v_mov_b32_e32 v2, s4
	v_mov_b32_e32 v3, s5
	ds_write_b32 v2, v147

; __device__ __forceinline__ unsigned cvtpk(float lo, float hi) { unsigned r; asm volatile("v_cvt_pk_bf16_f32 %0, %1, %2" : "=v"(r) : "v"(lo), "v"(hi)); return r; }
; __device__ __forceinline__ int crow(int r, int hi) { return (r & 3) + 8 * (r >> 2) + 4 * hi; }
; template <int DQ, bool WIN, int LDQ, int LDK> ...
;     ...
;     float rli[16]; bool fin = true;
; #pragma unroll
;     for (int r = 0; r < 16; ++r) { fin = fin && (lsum[r] < ATT_GUARD) && (lsum[r] > 0.f); rli[r] = __builtin_amdgcn_rcpf(lsum[r]); }
;     if (!__all(fin)) { if (lane == 0) *redo_flag = 1; }
;     bf16_t* Ow = Ob + (size_t)(wid * 32) * LDO;
; #pragma unroll
;     for (int r = 0; r < 16; ++r) { const int orow = crow(r, hi);
; #pragma unroll
;         for (int d0 = 0; d0 < 2; ++d0) Ow[(size_t)orow * LDO + d0 * 32 + r32] = (bf16_t)(cvtpk(o[d0][r] * rli[r], 0.f) & 0xffffu); }
;     __syncthreads();
.LBB0_456:
	s_or_b64 exec, exec, s[0:1]
	s_lshl_b32 s0, s6, 11
	s_add_u32 s0, s71, s0
	s_addc_u32 s1, s72, 0
	s_lshl_b32 s4, s11, 1
	s_add_u32 s42, s0, s4
	s_addc_u32 s43, s1, 0
	s_ashr_i32 s41, s40, 31
	v_rcp_f32_e32 v1, v1
	s_lshl_b64 s[0:1], s[40:41], 11
	s_add_u32 s0, s42, s0
	v_rcp_f32_e32 v52, v34
	s_addc_u32 s1, s43, s1
	v_lshlrev_b32_e32 v146, 1, v157
	v_rcp_f32_e32 v51, v35
	v_lshl_add_u64 v[34:35], s[0:1], 0, v[146:147]
	v_lshlrev_b32_e32 v146, 13, v156
	v_rcp_f32_e32 v49, v37
	v_rcp_f32_e32 v50, v36
	v_lshl_add_u64 v[36:37], v[34:35], 0, v[146:147]
	v_mul_f32_e32 v2, v2, v1
	v_mul_f32_e32 v1, v18, v1
	v_cvt_pk_bf16_f32 v2, v2, v147
	global_store_short v[36:37], v2, off offset:1024
	v_cvt_pk_bf16_f32 v1, v1, v147
	global_store_short v[36:37], v1, off offset:1088
	v_mul_f32_e32 v1, v3, v52
	v_cvt_pk_bf16_f32 v1, v1, v147
	global_store_short v[36:37], v1, off offset:3072
	v_mul_f32_e32 v1, v19, v52
	v_cvt_pk_bf16_f32 v1, v1, v147
	global_store_short v[36:37], v1, off offset:3136
	v_lshlrev_b32_e32 v146, 11, v159
	v_mul_f32_e32 v1, v4, v51
	v_lshl_add_u64 v[2:3], v[34:35], 0, v[146:147]
	v_cvt_pk_bf16_f32 v1, v1, v147
	global_store_short v[2:3], v1, off offset:1024
	v_mul_f32_e32 v1, v20, v51
	v_cvt_pk_bf16_f32 v1, v1, v147
	global_store_short v[2:3], v1, off offset:1088
	v_lshlrev_b32_e32 v146, 11, v160
	v_mul_f32_e32 v1, v5, v50
	v_lshl_add_u64 v[2:3], v[34:35], 0, v[146:147]
	v_cvt_pk_bf16_f32 v1, v1, v147
	global_store_short v[2:3], v1, off offset:1024
	v_mul_f32_e32 v1, v21, v50
	v_cvt_pk_bf16_f32 v1, v1, v147
	v_rcp_f32_e32 v38, v38
	global_store_short v[2:3], v1, off offset:1088
	v_lshlrev_b32_e32 v146, 11, v161
	v_mul_f32_e32 v1, v6, v49
	v_lshl_add_u64 v[2:3], v[34:35], 0, v[146:147]
	v_cvt_pk_bf16_f32 v1, v1, v147
	global_store_short v[2:3], v1, off offset:1024
	v_mul_f32_e32 v1, v22, v49
	v_cvt_pk_bf16_f32 v1, v1, v147
	v_rcp_f32_e32 v39, v39
	global_store_short v[2:3], v1, off offset:1088
	v_lshlrev_b32_e32 v146, 11, v162
	v_mul_f32_e32 v1, v7, v38
	v_lshl_add_u64 v[2:3], v[34:35], 0, v[146:147]
	v_cvt_pk_bf16_f32 v1, v1, v147
	global_store_short v[2:3], v1, off offset:1024
	v_mul_f32_e32 v1, v23, v38
	v_cvt_pk_bf16_f32 v1, v1, v147
	v_rcp_f32_e32 v40, v40
	global_store_short v[2:3], v1, off offset:1088
	v_lshlrev_b32_e32 v146, 11, v163
	v_mul_f32_e32 v1, v8, v39
	v_lshl_add_u64 v[2:3], v[34:35], 0, v[146:147]
	v_cvt_pk_bf16_f32 v1, v1, v147
	global_store_short v[2:3], v1, off offset:1024
	v_mul_f32_e32 v1, v24, v39
	v_cvt_pk_bf16_f32 v1, v1, v147
	v_rcp_f32_e32 v41, v41
	global_store_short v[2:3], v1, off offset:1088
	v_lshlrev_b32_e32 v146, 11, v164
	v_mul_f32_e32 v1, v9, v40
	v_lshl_add_u64 v[2:3], v[34:35], 0, v[146:147]
	v_cvt_pk_bf16_f32 v1, v1, v147
	global_store_short v[2:3], v1, off offset:1024
	v_mul_f32_e32 v1, v25, v40
	v_cvt_pk_bf16_f32 v1, v1, v147
	v_rcp_f32_e32 v42, v42
	global_store_short v[2:3], v1, off offset:1088
	v_lshlrev_b32_e32 v146, 11, v165
	v_mul_f32_e32 v1, v10, v41
	v_lshl_add_u64 v[2:3], v[34:35], 0, v[146:147]
	v_cvt_pk_bf16_f32 v1, v1, v147
	global_store_short v[2:3], v1, off offset:1024
	v_mul_f32_e32 v1, v26, v41
	v_cvt_pk_bf16_f32 v1, v1, v147
	v_rcp_f32_e32 v43, v43
	global_store_short v[2:3], v1, off offset:1088
	v_lshlrev_b32_e32 v146, 11, v166
	v_mul_f32_e32 v1, v11, v42
	v_lshl_add_u64 v[2:3], v[34:35], 0, v[146:147]
	v_cvt_pk_bf16_f32 v1, v1, v147
	global_store_short v[2:3], v1, off offset:1024
	v_mul_f32_e32 v1, v27, v42
	v_cvt_pk_bf16_f32 v1, v1, v147
	v_rcp_f32_e32 v44, v44
	global_store_short v[2:3], v1, off offset:1088
	v_lshlrev_b32_e32 v146, 11, v167
	v_mul_f32_e32 v1, v12, v43
	v_lshl_add_u64 v[2:3], v[34:35], 0, v[146:147]
	v_cvt_pk_bf16_f32 v1, v1, v147
	global_store_short v[2:3], v1, off offset:1024
	v_mul_f32_e32 v1, v28, v43
	v_cvt_pk_bf16_f32 v1, v1, v147
	v_rcp_f32_e32 v45, v45
	global_store_short v[2:3], v1, off offset:1088
	v_lshlrev_b32_e32 v146, 11, v168
	v_mul_f32_e32 v1, v13, v44
	v_lshl_add_u64 v[2:3], v[34:35], 0, v[146:147]
	v_cvt_pk_bf16_f32 v1, v1, v147
	global_store_short v[2:3], v1, off offset:1024
	v_mul_f32_e32 v1, v29, v44
	v_cvt_pk_bf16_f32 v1, v1, v147
	v_rcp_f32_e32 v46, v46
	global_store_short v[2:3], v1, off offset:1088
	v_lshlrev_b32_e32 v146, 11, v169
	v_mul_f32_e32 v1, v14, v45
	v_lshl_add_u64 v[2:3], v[34:35], 0, v[146:147]
	v_cvt_pk_bf16_f32 v1, v1, v147
	global_store_short v[2:3], v1, off offset:1024
	v_mul_f32_e32 v1, v30, v45
	v_cvt_pk_bf16_f32 v1, v1, v147
	v_rcp_f32_e32 v47, v47
	global_store_short v[2:3], v1, off offset:1088
	v_lshlrev_b32_e32 v146, 11, v170
	v_mul_f32_e32 v1, v15, v46
	v_lshl_add_u64 v[2:3], v[34:35], 0, v[146:147]
	v_cvt_pk_bf16_f32 v1, v1, v147
	global_store_short v[2:3], v1, off offset:1024
	v_mul_f32_e32 v1, v31, v46
	v_cvt_pk_bf16_f32 v1, v1, v147
	v_rcp_f32_e32 v48, v48
	global_store_short v[2:3], v1, off offset:1088
	v_lshlrev_b32_e32 v146, 11, v171
	v_mul_f32_e32 v1, v16, v47
	v_lshl_add_u64 v[2:3], v[34:35], 0, v[146:147]
	v_cvt_pk_bf16_f32 v1, v1, v147
	global_store_short v[2:3], v1, off offset:1024
	v_mul_f32_e32 v1, v32, v47
	v_cvt_pk_bf16_f32 v1, v1, v147
	global_store_short v[2:3], v1, off offset:1088
	v_lshlrev_b32_e32 v146, 11, v172
	v_mul_f32_e32 v1, v17, v48
	v_lshl_add_u64 v[2:3], v[34:35], 0, v[146:147]
	v_cvt_pk_bf16_f32 v1, v1, v147
	s_cmp_lg_u32 s97, -1
	s_mov_b64 s[0:1], src_shared_base
	global_store_short v[2:3], v1, off offset:1024
	v_mul_f32_e32 v1, v33, v48
	s_cselect_b32 s4, s97, 0
	s_cselect_b32 s0, s1, 0
	v_cvt_pk_bf16_f32 v1, v1, v147
	global_store_short v[2:3], v1, off offset:1088
	v_mov_b32_e32 v2, s4
	v_mov_b32_e32 v3, s0
	s_waitcnt lgkmcnt(0)
	s_barrier
; __device__ __forceinline__ int otid() { int t = threadIdx.x; asm volatile("" : "+v"(t)); return t; }
; __device__ __forceinline__ int v_st(int k, int c) { const int kk = (k & ~0xC) | ((k & 4) << 1) | ((k & 8) >> 1); return ((kk >> 3) * 2 + (c >> 5)) * 512 + ((kk & 7) * 32 + (c & 31)) * 2; }
; __device__ __forceinline__ int v_rd_base(int lane) { return ((lane & 3) << 3) | (((lane >> 2) & 3) << 6) | (((lane >> 4) & 1) << 5) | (((lane >> 5) & 1) << 8); }
; #define SLOAD(i, k0) do { st_[i].vs = *reinterpret_cast<const bf16x8*>(&Vh[(size_t)((k0) + sr) * LDK + sc]); \
;     st_[i].ks = *reinterpret_cast<const bf16x8*>(&Kh[(size_t)((k0) + sr) * LDK + sc]); \
;     if (DQ == 96) st_[i].kr = *reinterpret_cast<const bf16x8*>(&Kr[(size_t)((k0) + sr2) * 32 + sc2]); } while (0)
; #define SWRITE(b, i) do { *(bf16x8*)(V_lds + (b) * SHM_V + vst0) = st_[i].vs; *(bf16x8*)(K_lds + (b) * SHM_K + kst0) = st_[i].ks; \
;     if (DQ == 96) { if (tid < 256) *(bf16x8*)(K_lds + (b) * SHM_K + kst2) = st_[i].kr; } } while (0)
; template <int DQ, bool WIN, int LDQ, int LDK> ...
;     ...
;     const int tid = otid(), wid = __builtin_amdgcn_readfirstlane(tid >> 6), lane = tid & 63, r32 = lane & 31, hi = lane >> 5;
;     char* V_lds = lds; char* K_lds = lds + 2 * SHM_V;
;     float* wsf = (float*)(lds + 2 * SHM_V + 2 * SHM_K) + wid * 64; float* li_l = wsf; float* al_l = wsf + 32;
;     float m_reg = -1e30f, l_reg = 0; f32x16 o[2] = {}; bf16x8 qr[ND];
;     const bf16_t* Qw = Qb + (size_t)(wid * 32 + r32) * LDQ + hi * 8;
; #pragma unroll
;     for (int d0 = 0; d0 < ND; ++d0) qr[d0] = *reinterpret_cast<const bf16x8*>(Qw + d0 * 16);
;     const int sr = tid >> 3, sc = (tid & 7) * 8, vst0 = v_st(sr, sc);
;     const int kst0 = sr * KROW + sc * 2;
;     const int sr2 = (tid & 255) >> 2, sc2 = (tid & 3) * 8; const int kst2 = sr2 * KROW + 128 + sc2 * 2;
;     const int vb0 = (int)(uintptr_t)V_lds + v_rd_base(lane);
;     const int qrow = q0 + wid * 32 + r32;
;     struct { bf16x8 vs, ks, kr; } st_[2];
;     ...
;     f32x16 pA0, pA1, pB0, pB1; float mnA, mnB, alA, alB; bf16x8 pa0, pa1, pa2, pa3;
;     constexpr int SE = 0, SO = 1;
;     SLOAD(SE, KBASE(0)); asm volatile("s_waitcnt vmcnt(0)" ::: "memory"); SWRITE(0, SE); __syncthreads();
; template <int DQ, bool WIN, int LDQ, int LDK> ...
;     ...
;     const int redo = __builtin_amdgcn_readfirstlane(*redo_flag);
;     __syncthreads();
;     return redo;
	ds_read_b32 v1, v2
	s_mov_b64 s[0:1], 0
	s_mov_b64 s[8:9], 0
	s_waitcnt lgkmcnt(0)
	s_barrier
	v_readfirstlane_b32 s4, v1
	s_cmp_eq_u32 s4, 0
	s_cbranch_scc1 .LBB0_488
	v_mov_b32_e32 v65, v181
	global_load_dword v134, v147, s[34:35]
	s_nop 0
	v_ashrrev_i32_e32 v66, 3, v65
	v_lshlrev_b32_e32 v4, 3, v65
	v_add_u32_e32 v34, v66, v155
	v_and_b32_e32 v1, 56, v4
	v_mad_i64_i32 v[2:3], s[4:5], v34, s83, 0
	v_or_b32_e32 v2, v2, v1
	v_lshl_add_u64 v[2:3], v[2:3], 1, s[20:21]
	global_load_dwordx4 v[114:117], v[2:3], off offset:2816
	global_load_dwordx4 v[118:121], v[2:3], off offset:2560
	v_readfirstlane_b32 s8, v65
	s_ashr_i32 s6, s8, 1
	v_mov_b32_e32 v2, s6
	v_bfe_u32 v135, v65, 5, 1
	v_bfi_b32 v5, s79, v2, v65
	v_mov_b64_e32 v[2:3], s[22:23]
	v_mad_i64_i32 v[2:3], s[4:5], v5, s78, v[2:3]
	v_lshlrev_b32_e32 v146, 4, v135
	v_lshl_add_u64 v[2:3], v[2:3], 0, v[146:147]
	global_load_dwordx4 v[110:113], v[2:3], off offset:1536
	global_load_dwordx4 v[106:109], v[2:3], off offset:1568
	global_load_dwordx4 v[102:105], v[2:3], off offset:1600
	global_load_dwordx4 v[98:101], v[2:3], off offset:1632
	v_and_b32_e32 v136, 31, v65
	v_and_b32_e32 v5, 0x1fffff0, v66
	v_lshlrev_b32_e32 v6, 1, v66
	v_lshrrev_b32_e32 v7, 1, v66
	v_and_b32_e32 v8, 3, v66
	v_mad_u32_u24 v3, v136, s82, 0
	v_and_or_b32 v5, v6, 8, v5
	v_lshlrev_b32_e32 v2, 1, v1
	v_bfe_u32 v4, v4, 5, 1
	v_and_or_b32 v6, v7, 4, v8
	v_add_u32_e32 v165, v3, v146
	v_lshrrev_b32_e32 v5, 2, v5
	v_and_b32_e32 v7, 48, v2
	v_mad_u64_u32 v[2:3], s[4:5], v66, s82, v[2:3]
	v_or_b32_e32 v3, v5, v4
	v_lshl_or_b32 v4, v6, 6, v7
	v_add_u32_e32 v166, 0, v2
	v_lshl_or_b32 v2, v3, 9, v4
	v_add_u32_e32 v167, 0, v2
	s_waitcnt vmcnt(0)
	v_or_b32_e32 v35, s63, v136
	s_andn2_b32 s6, s6, 31
	v_add_u32_e32 v164, s6, v35
	v_lshlrev_b32_e32 v162, 2, v135
	v_sub_u32_e32 v48, v164, v155
	v_sub_u32_e32 v35, v48, v162
	v_not_b32_e32 v163, v162
	v_add_u32_e32 v49, v48, v163
	v_or_b32_e32 v141, 2, v162
	v_sub_u32_e32 v50, v48, v141
	v_or_b32_e32 v140, 3, v162
	v_sub_u32_e32 v51, v48, v140
	v_or_b32_e32 v138, 8, v162
	v_add_u32_e32 v55, 0xffffff7f, v51
	v_sub_u32_e32 v52, v48, v138
	v_or_b32_e32 v139, 9, v162
	v_sub_u32_e32 v53, v48, v139
	v_or_b32_e32 v137, 10, v162
	v_sub_u32_e32 v54, v48, v137
	v_or_b32_e32 v155, 11, v162
	v_or_b32_e32 v151, 16, v162
	v_or_b32_e32 v150, 17, v162
	v_or_b32_e32 v149, 18, v162
	v_or_b32_e32 v148, 19, v162
	v_or_b32_e32 v145, 24, v162
	v_or_b32_e32 v144, 25, v162
	v_or_b32_e32 v143, 26, v162
	v_or_b32_e32 v142, 27, v162
	s_waitcnt vmcnt(5)
	ds_write_b128 v167, v[114:117]
	s_waitcnt vmcnt(4)
	ds_write_b128 v166, v[118:121] offset:16384
	s_waitcnt lgkmcnt(0)
	s_barrier
; __device__ __forceinline__ int crow(int r, int hi) { return (r & 3) + 8 * (r >> 2) + 4 * hi; }
; #define SLOAD(i, k0) do { st_[i].vs = *reinterpret_cast<const bf16x8*>(&Vh[(size_t)((k0) + sr) * LDK + sc]); \
;     st_[i].ks = *reinterpret_cast<const bf16x8*>(&Kh[(size_t)((k0) + sr) * LDK + sc]); \
;     if (DQ == 96) st_[i].kr = *reinterpret_cast<const bf16x8*>(&Kr[(size_t)((k0) + sr2) * 32 + sc2]); } while (0)
; #define SWRITE(b, i) do { *(bf16x8*)(V_lds + (b) * SHM_V + vst0) = st_[i].vs; *(bf16x8*)(K_lds + (b) * SHM_K + kst0) = st_[i].ks; \
;     if (DQ == 96) { if (tid < 256) *(bf16x8*)(K_lds + (b) * SHM_K + kst2) = st_[i].kr; } } while (0)
; #define SLOAD(i, k0) do { st_[i].vs = *reinterpret_cast<const bf16x8*>(&Vh[(size_t)((k0) + sr) * LDK + sc]); \
;     st_[i].ks = *reinterpret_cast<const bf16x8*>(&Kh[(size_t)((k0) + sr) * LDK + sc]); \
;     if (DQ == 96) st_[i].kr = *reinterpret_cast<const bf16x8*>(&Kr[(size_t)((k0) + sr2) * 32 + sc2]); } while (0)
; template <int DQ, bool WIN>
; __device__ __forceinline__ void partialSM_s(f32x16& p0, f32x16& p1, float& m_reg, float& mn, float& alpha, int dlt, int hi) {
;     constexpr float C = 1.0f, SCALE = 1.0f / 1.4426950408889634f;
;     if (WIN) {
; #pragma unroll
;         for (int r = 0; r < 16; ++r) { const int d0 = dlt - crow(r, hi), d1 = d0 - 32;
;             if (d0 > 128 || d0 < -128) p0[r] = -INFINITY;
;             if (d1 > 128 || d1 < -128) p1[r] = -INFINITY; }
;     }
;     float pmax = p0[0];
; #pragma unroll
;     for (int r = 1; r < 16; ++r) pmax = fmaxf(pmax, p0[r]);
; #pragma unroll
;     for (int r = 0; r < 16; ++r) pmax = fmaxf(pmax, p1[r]);
;     { auto rr = __builtin_amdgcn_permlane32_swap(__float_as_uint(pmax), __float_as_uint(pmax), false, false);
;       pmax = fmaxf(__uint_as_float(rr[0]), __uint_as_float(rr[1])); }
;     if (__builtin_expect(__all(pmax - m_reg <= ATT_THR / SCALE), 1)) { mn = m_reg; alpha = 1.f; }
; template <int DQ, bool WIN, int LDQ, int LDK> ...
;     ...
;     SLOAD(SE, KBASE(0)); asm volatile("s_waitcnt vmcnt(0)" ::: "memory"); SWRITE(0, SE); __syncthreads();
;     qkt_s<DQ>(pA0, pA1, K_lds, qr, r32, hi); partialSM_s<DQ, WIN>(pA0, pA1, m_reg, mnA, alA, qrow - KBASE(0), hi);
	ds_read_b128 v[2:5], v165 offset:16384
	ds_read_b128 v[36:39], v165 offset:16416
	ds_read_b128 v[18:21], v165 offset:20992
	ds_read_b128 v[40:43], v165 offset:21024
	s_waitcnt vmcnt(3) lgkmcnt(3)
	v_mfma_f32_32x32x16_bf16 v[2:17], v[2:5], v[110:113], 0
	s_waitcnt lgkmcnt(1)
	v_mfma_f32_32x32x16_bf16 v[18:33], v[18:21], v[110:113], 0
	s_waitcnt vmcnt(2)
	v_mfma_f32_32x32x16_bf16 v[2:17], v[36:39], v[106:109], v[2:17]
	ds_read_b128 v[36:39], v165 offset:16448
	s_waitcnt lgkmcnt(1)
	v_mfma_f32_32x32x16_bf16 v[18:33], v[40:43], v[106:109], v[18:33]
	ds_read_b128 v[40:43], v165 offset:21056
	ds_read_b128 v[44:47], v165 offset:16480
	s_waitcnt vmcnt(1) lgkmcnt(2)
	v_mfma_f32_32x32x16_bf16 v[2:17], v[36:39], v[102:105], v[2:17]
	ds_read_b128 v[36:39], v165 offset:21088
	s_waitcnt lgkmcnt(2)
	v_mfma_f32_32x32x16_bf16 v[18:33], v[40:43], v[102:105], v[18:33]
	v_add_u32_e32 v40, 0xffffff7f, v35
	v_add_u32_e32 v41, 0xffffff5f, v35
	v_cmp_lt_u32_e32 vcc, s84, v40
	v_add_u32_e32 v42, 0xffffff7f, v49
	v_add_u32_e32 v43, 0xffffff5f, v49
	v_add_u32_e32 v49, 0xffffff7f, v50
	v_add_u32_e32 v50, 0xffffff5f, v50
	s_waitcnt vmcnt(0) lgkmcnt(1)
	v_mfma_f32_32x32x16_bf16 v[2:17], v[44:47], v[98:101], v[2:17]
	v_add_u32_e32 v44, 0xffffff5f, v51
	v_add_u32_e32 v45, 0xffffff7f, v52
	v_add_u32_e32 v46, 0xffffff5f, v52
	v_add_u32_e32 v47, 0xffffff7f, v53
	v_add_u32_e32 v51, 0xffffff5f, v53
	v_add_u32_e32 v52, 0xffffff7f, v54
	v_add_u32_e32 v53, 0xffffff5f, v54
	s_waitcnt lgkmcnt(0)
	v_mfma_f32_32x32x16_bf16 v[18:33], v[36:39], v[98:101], v[18:33]
	s_nop 2
	v_cndmask_b32_e32 v35, v153, v2, vcc
	v_cmp_lt_u32_e32 vcc, s84, v41
	v_sub_u32_e32 v2, v48, v155
	s_nop 5
	v_cndmask_b32_e32 v18, v153, v18, vcc
	v_cmp_lt_u32_e32 vcc, s84, v42
	s_nop 1
	v_cndmask_b32_e32 v36, v153, v3, vcc
	v_cmp_lt_u32_e32 vcc, s84, v43
	v_add_u32_e32 v3, 0xffffff7f, v2
	v_add_u32_e32 v2, 0xffffff5f, v2
	v_cndmask_b32_e32 v19, v153, v19, vcc
	v_cmp_lt_u32_e32 vcc, s84, v49
	s_nop 1
	v_cndmask_b32_e32 v37, v153, v4, vcc
	v_cmp_lt_u32_e32 vcc, s84, v50
	s_nop 1
	v_cndmask_b32_e32 v20, v153, v20, vcc
	v_cmp_lt_u32_e32 vcc, s84, v55
	s_nop 1
	v_cndmask_b32_e32 v38, v153, v5, vcc
	v_cmp_lt_u32_e32 vcc, s84, v44
	s_nop 1
	v_cndmask_b32_e32 v21, v153, v21, vcc
	v_cmp_lt_u32_e32 vcc, s84, v45
	s_nop 1
	v_cndmask_b32_e32 v39, v153, v6, vcc
	v_cmp_lt_u32_e32 vcc, s84, v46
	s_nop 1
	v_cndmask_b32_e32 v22, v153, v22, vcc
	v_cmp_lt_u32_e32 vcc, s84, v47
	s_nop 1
	v_cndmask_b32_e32 v40, v153, v7, vcc
	v_cmp_lt_u32_e32 vcc, s84, v51
	s_nop 1
	v_cndmask_b32_e32 v23, v153, v23, vcc
	v_cmp_lt_u32_e32 vcc, s84, v52
	s_nop 1
	v_cndmask_b32_e32 v41, v153, v8, vcc
	v_cmp_lt_u32_e32 vcc, s84, v53
	s_nop 1
	v_cndmask_b32_e32 v24, v153, v24, vcc
	v_cmp_lt_u32_e32 vcc, s84, v3
	s_nop 1
	v_cndmask_b32_e32 v42, v153, v9, vcc
	v_cmp_lt_u32_e32 vcc, s84, v2
	v_sub_u32_e32 v2, v48, v151
	v_add_u32_e32 v3, 0xffffff7f, v2
	v_cndmask_b32_e32 v25, v153, v25, vcc
	v_cmp_lt_u32_e32 vcc, s84, v3
	v_add_u32_e32 v2, 0xffffff5f, v2
	s_nop 0
	v_cndmask_b32_e32 v43, v153, v10, vcc
	v_cmp_lt_u32_e32 vcc, s84, v2
	v_sub_u32_e32 v2, v48, v150
	v_add_u32_e32 v3, 0xffffff7f, v2
	v_cndmask_b32_e32 v10, v153, v26, vcc
	v_cmp_lt_u32_e32 vcc, s84, v3
	v_add_u32_e32 v2, 0xffffff5f, v2
	s_nop 0
	v_cndmask_b32_e32 v26, v153, v11, vcc
	v_cmp_lt_u32_e32 vcc, s84, v2
	v_sub_u32_e32 v2, v48, v149
	v_add_u32_e32 v3, 0xffffff7f, v2
	v_cndmask_b32_e32 v11, v153, v27, vcc
	v_cmp_lt_u32_e32 vcc, s84, v3
	v_add_u32_e32 v2, 0xffffff5f, v2
	s_nop 0
	v_cndmask_b32_e32 v27, v153, v12, vcc
	v_cmp_lt_u32_e32 vcc, s84, v2
	v_sub_u32_e32 v2, v48, v148
	v_add_u32_e32 v3, 0xffffff7f, v2
	v_cndmask_b32_e32 v12, v153, v28, vcc
	v_cmp_lt_u32_e32 vcc, s84, v3
	v_add_u32_e32 v2, 0xffffff5f, v2
	s_nop 0
	v_cndmask_b32_e32 v28, v153, v13, vcc
	v_cmp_lt_u32_e32 vcc, s84, v2
	v_sub_u32_e32 v2, v48, v145
	v_add_u32_e32 v3, 0xffffff7f, v2
	v_cndmask_b32_e32 v13, v153, v29, vcc
	v_cmp_lt_u32_e32 vcc, s84, v3
	v_add_u32_e32 v2, 0xffffff5f, v2
	s_nop 0
	v_cndmask_b32_e32 v29, v153, v14, vcc
	v_cmp_lt_u32_e32 vcc, s84, v2
	v_sub_u32_e32 v2, v48, v144
	v_add_u32_e32 v3, 0xffffff7f, v2
	v_cndmask_b32_e32 v14, v153, v30, vcc
	v_cmp_lt_u32_e32 vcc, s84, v3
	v_add_u32_e32 v2, 0xffffff5f, v2
	s_nop 0
	v_cndmask_b32_e32 v30, v153, v15, vcc
	v_cmp_lt_u32_e32 vcc, s84, v2
	v_sub_u32_e32 v2, v48, v143
	v_add_u32_e32 v3, 0xffffff7f, v2
	v_cndmask_b32_e32 v15, v153, v31, vcc
	v_cmp_lt_u32_e32 vcc, s84, v3
	v_add_u32_e32 v2, 0xffffff5f, v2
	s_nop 0
	v_cndmask_b32_e32 v16, v153, v16, vcc
	v_cmp_lt_u32_e32 vcc, s84, v2
	v_sub_u32_e32 v2, v48, v142
	v_add_u32_e32 v3, 0xffffff7f, v2
	v_cndmask_b32_e32 v31, v153, v32, vcc
	v_cmp_lt_u32_e32 vcc, s84, v3
	v_add_u32_e32 v2, 0xffffff5f, v2
	v_max_f32_e32 v3, v35, v35
	v_cndmask_b32_e32 v17, v153, v17, vcc
	v_cmp_lt_u32_e32 vcc, s84, v2
	v_max_f32_e32 v2, v36, v36
	v_max_f32_e32 v2, v3, v2
	v_max3_f32 v2, v2, v37, v38
	v_max3_f32 v2, v2, v39, v40
	v_max3_f32 v2, v2, v41, v42
	v_max3_f32 v2, v2, v43, v26
	v_max3_f32 v2, v2, v27, v28
	v_max3_f32 v2, v2, v29, v30
	v_max3_f32 v2, v2, v16, v17
	v_max3_f32 v2, v2, v18, v19
	v_max3_f32 v2, v2, v20, v21
	v_max3_f32 v2, v2, v22, v23
	v_max3_f32 v2, v2, v24, v25
	v_max3_f32 v2, v2, v10, v11
	v_max3_f32 v2, v2, v12, v13
	v_cndmask_b32_e32 v32, v153, v33, vcc
	v_max3_f32 v2, v2, v14, v15
	v_max3_f32 v2, v2, v31, v32
	v_mov_b32_e32 v3, v2
	s_nop 1
	v_permlane32_swap_b32_e32 v2, v3
	v_max_f32_e32 v3, v3, v3
	v_max_f32_e32 v2, v2, v2
	v_max_f32_e32 v2, v2, v3
	v_add_f32_e32 v3, 0x7149f2ca, v2
	v_cmp_ge_f32_e32 vcc, s89, v3
	s_cmp_eq_u64 vcc, exec
	s_cbranch_scc0 .LBB0_520
	v_mov_b32_e32 v169, 1.0
	v_mov_b32_e32 v156, 0xf149f2ca

; template <int DQ, bool WIN, int LDQ, int LDK> ...
;     ...
;     volatile int* redo_flag = (volatile int*)(lds + 2 * SHM_V + 2 * SHM_K + 8 * 64 * 4);
;     if (tid == 0) *redo_flag = 0;
; __device__ __forceinline__ void phase_attn0(const Params& p, char* lds) {
;     ...
;         if (!win) {
;             if (attn_body<64, false, 1536, 1536>(proj + (tok0 + q0) * 1536 + hq * 64, proj + tok0 * 1536 + 512 + kvh * 64, nullptr, proj + tok0 * 1536 + 640 + kvh * 64,
.LBB0_488:
	s_and_b64 vcc, exec, s[0:1]
	s_cbranch_vccz .LBB0_518
	v_mov_b32_e32 v34, v181
	s_nop 0
	v_readfirstlane_b32 s20, v34
	v_cmp_eq_u32_e32 vcc, 0, v34
	s_and_saveexec_b64 s[0:1], vcc
	s_cbranch_execz .LBB0_491
	s_mov_b64 s[4:5], src_shared_base
	s_cmp_lg_u32 s97, -1
	s_cselect_b32 s4, s97, 0
	s_cselect_b32 s5, s5, 0
	v_mov_b32_e32 v2, s4
	v_mov_b32_e32 v3, s5
	ds_write_b32 v2, v147

; __device__ __forceinline__ unsigned cvtpk(float lo, float hi) { unsigned r; asm volatile("v_cvt_pk_bf16_f32 %0, %1, %2" : "=v"(r) : "v"(lo), "v"(hi)); return r; }
; __device__ __forceinline__ int crow(int r, int hi) { return (r & 3) + 8 * (r >> 2) + 4 * hi; }
; template <int DQ, bool WIN, int LDQ, int LDK> ...
;     ...
;     float rli[16]; bool fin = true;
; #pragma unroll
;     for (int r = 0; r < 16; ++r) { fin = fin && (lsum[r] < ATT_GUARD) && (lsum[r] > 0.f); rli[r] = __builtin_amdgcn_rcpf(lsum[r]); }
;     if (!__all(fin)) { if (lane == 0) *redo_flag = 1; }
;     bf16_t* Ow = Ob + (size_t)(wid * 32) * LDO;
; #pragma unroll
;     for (int r = 0; r < 16; ++r) { const int orow = crow(r, hi);
; #pragma unroll
;         for (int d0 = 0; d0 < 2; ++d0) Ow[(size_t)orow * LDO + d0 * 32 + r32] = (bf16_t)(cvtpk(o[d0][r] * rli[r], 0.f) & 0xffffu); }
;     __syncthreads();
;     const int redo = __builtin_amdgcn_readfirstlane(*redo_flag);
;     __syncthreads();
;     return redo;
.LBB0_497:
	s_or_b64 exec, exec, s[0:1]
	s_mov_b64 s[0:1], src_shared_base
	s_lshl_b32 s0, s10, 11
	s_add_u32 s0, s71, s0
	s_addc_u32 s21, s72, 0
	s_lshl_b32 s10, s11, 1
	s_add_u32 s10, s0, s10
	s_addc_u32 s11, s21, 0
	v_rcp_f32_e32 v53, v34
	s_ashr_i32 s21, s20, 31
	s_lshl_b64 s[20:21], s[20:21], 11
	s_add_u32 s20, s10, s20
	s_addc_u32 s21, s11, s21
	v_lshlrev_b32_e32 v146, 1, v150
	v_rcp_f32_e32 v50, v37
	v_rcp_f32_e32 v51, v36
	v_rcp_f32_e32 v52, v35
	v_lshlrev_b32_e32 v34, 13, v1
	v_lshl_add_u64 v[36:37], s[20:21], 0, v[146:147]
	v_mov_b32_e32 v35, v147
	v_mul_f32_e32 v1, v2, v53
	v_lshl_add_u64 v[34:35], v[36:37], 0, v[34:35]
	v_cvt_pk_bf16_f32 v1, v1, v147
	global_store_short v[34:35], v1, off
	v_mul_f32_e32 v1, v18, v53
	v_cvt_pk_bf16_f32 v1, v1, v147
	global_store_short v[34:35], v1, off offset:64
	v_mul_f32_e32 v1, v3, v52
	v_cvt_pk_bf16_f32 v1, v1, v147
	global_store_short v[34:35], v1, off offset:2048
	v_mul_f32_e32 v1, v19, v52
	v_cvt_pk_bf16_f32 v1, v1, v147
	global_store_short v[34:35], v1, off offset:2112
	v_mul_f32_e32 v1, v4, v51
	v_add_co_u32_e32 v2, vcc, s91, v34
	v_cvt_pk_bf16_f32 v1, v1, v147
	v_rcp_f32_e32 v38, v38
	s_nop 0
	v_addc_co_u32_e32 v3, vcc, 0, v35, vcc
	global_store_short v[2:3], v1, off
	v_mul_f32_e32 v1, v20, v51
	v_cvt_pk_bf16_f32 v1, v1, v147
	global_store_short v[2:3], v1, off offset:64
	v_mul_f32_e32 v1, v5, v50
	v_cvt_pk_bf16_f32 v1, v1, v147
	global_store_short v[2:3], v1, off offset:2048
	v_mul_f32_e32 v1, v21, v50
	v_cvt_pk_bf16_f32 v1, v1, v147
	global_store_short v[2:3], v1, off offset:2112
	v_add_co_u32_e32 v2, vcc, s92, v34
	v_rcp_f32_e32 v39, v39
	s_nop 0
	v_addc_co_u32_e32 v3, vcc, 0, v35, vcc
	v_mul_f32_e32 v1, v6, v38
	v_add_co_u32_e32 v4, vcc, s93, v34
	v_cvt_pk_bf16_f32 v1, v1, v147
	v_rcp_f32_e32 v40, v40
	s_nop 0
	v_addc_co_u32_e32 v5, vcc, 0, v35, vcc
	global_store_short v[4:5], v1, off offset:-4096
	v_mul_f32_e32 v1, v22, v38
	v_cvt_pk_bf16_f32 v1, v1, v147
	global_store_short v[2:3], v1, off offset:64
	v_mul_f32_e32 v1, v7, v39
	v_cvt_pk_bf16_f32 v1, v1, v147
	global_store_short v[2:3], v1, off offset:2048
	v_mul_f32_e32 v1, v23, v39
	v_cvt_pk_bf16_f32 v1, v1, v147
	v_rcp_f32_e32 v41, v41
	global_store_short v[2:3], v1, off offset:2112
	v_mul_f32_e32 v1, v8, v40
	v_cvt_pk_bf16_f32 v1, v1, v147
	global_store_short v[4:5], v1, off
	v_mul_f32_e32 v1, v24, v40
	v_cvt_pk_bf16_f32 v1, v1, v147
	v_rcp_f32_e32 v42, v42
	global_store_short v[4:5], v1, off offset:64
	v_mul_f32_e32 v1, v9, v41
	v_cvt_pk_bf16_f32 v1, v1, v147
	global_store_short v[4:5], v1, off offset:2048
	v_mul_f32_e32 v1, v25, v41
	v_add_co_u32_e32 v2, vcc, s94, v34
	v_cvt_pk_bf16_f32 v1, v1, v147
	v_rcp_f32_e32 v43, v43
	s_nop 0
	v_addc_co_u32_e32 v3, vcc, 0, v35, vcc
	global_store_short v[4:5], v1, off offset:2112
	v_mul_f32_e32 v1, v10, v42
	v_add_co_u32_e32 v4, vcc, s77, v34
	v_cvt_pk_bf16_f32 v1, v1, v147
	v_rcp_f32_e32 v44, v44
	s_nop 0
	v_addc_co_u32_e32 v5, vcc, 0, v35, vcc
	global_store_short v[4:5], v1, off offset:-4096
	v_mul_f32_e32 v1, v26, v42
	v_cvt_pk_bf16_f32 v1, v1, v147
	global_store_short v[2:3], v1, off offset:64
	v_mul_f32_e32 v1, v11, v43
	v_cvt_pk_bf16_f32 v1, v1, v147
	global_store_short v[2:3], v1, off offset:2048
	v_mul_f32_e32 v1, v27, v43
	v_cvt_pk_bf16_f32 v1, v1, v147
	v_rcp_f32_e32 v45, v45
	global_store_short v[2:3], v1, off offset:2112
	v_mul_f32_e32 v1, v12, v44
	v_cvt_pk_bf16_f32 v1, v1, v147
	global_store_short v[4:5], v1, off
	v_mul_f32_e32 v1, v28, v44
	v_cvt_pk_bf16_f32 v1, v1, v147
	v_rcp_f32_e32 v46, v46
	global_store_short v[4:5], v1, off offset:64
	v_mul_f32_e32 v1, v13, v45
	v_cvt_pk_bf16_f32 v1, v1, v147
	global_store_short v[4:5], v1, off offset:2048
	v_mul_f32_e32 v1, v29, v45
	v_add_co_u32_e32 v2, vcc, s95, v34
	v_cvt_pk_bf16_f32 v1, v1, v147
	v_rcp_f32_e32 v47, v47
	s_nop 0
	v_addc_co_u32_e32 v3, vcc, 0, v35, vcc
	global_store_short v[4:5], v1, off offset:2112
	v_mul_f32_e32 v1, v14, v46
	v_add_co_u32_e32 v4, vcc, s96, v34
	v_cvt_pk_bf16_f32 v1, v1, v147
	v_rcp_f32_e32 v48, v48
	s_nop 0
	v_addc_co_u32_e32 v5, vcc, 0, v35, vcc
	global_store_short v[4:5], v1, off offset:-4096
	v_mul_f32_e32 v1, v30, v46
	v_cvt_pk_bf16_f32 v1, v1, v147
	global_store_short v[2:3], v1, off offset:64
	v_mul_f32_e32 v1, v15, v47
	v_cvt_pk_bf16_f32 v1, v1, v147
	global_store_short v[2:3], v1, off offset:2048
	v_mul_f32_e32 v1, v31, v47
	v_cvt_pk_bf16_f32 v1, v1, v147
	v_rcp_f32_e32 v49, v49
	global_store_short v[2:3], v1, off offset:2112
	v_mul_f32_e32 v1, v16, v48
	v_cvt_pk_bf16_f32 v1, v1, v147
	global_store_short v[4:5], v1, off
	v_mul_f32_e32 v1, v32, v48
	v_cvt_pk_bf16_f32 v1, v1, v147
	global_store_short v[4:5], v1, off offset:64
	v_mul_f32_e32 v1, v17, v49
	v_cvt_pk_bf16_f32 v1, v1, v147
	s_cmp_lg_u32 s97, -1
	global_store_short v[4:5], v1, off offset:2048
	v_mul_f32_e32 v1, v33, v49
	s_cselect_b32 s0, s97, 0
	s_cselect_b32 s1, s1, 0
	v_cvt_pk_bf16_f32 v1, v1, v147
	v_mov_b32_e32 v2, s0
	v_mov_b32_e32 v3, s1
	global_store_short v[4:5], v1, off offset:2112
	s_waitcnt lgkmcnt(0)
	s_barrier
	ds_read_b32 v1, v2
	s_waitcnt lgkmcnt(0)
	s_barrier
	v_readfirstlane_b32 s0, v1
	s_cmp_eq_u32 s0, 0
	s_cbranch_scc1 .LBB0_518
; __device__ __forceinline__ int otid() { int t = threadIdx.x; asm volatile("" : "+v"(t)); return t; }
; __device__ __forceinline__ int v_st(int k, int c) { const int kk = (k & ~0xC) | ((k & 4) << 1) | ((k & 8) >> 1); return ((kk >> 3) * 2 + (c >> 5)) * 512 + ((kk & 7) * 32 + (c & 31)) * 2; }
; __device__ __forceinline__ int v_rd_base(int lane) { return ((lane & 3) << 3) | (((lane >> 2) & 3) << 6) | (((lane >> 4) & 1) << 5) | (((lane >> 5) & 1) << 8); }
; #define SLOAD(i, k0) do { st_[i].vs = *reinterpret_cast<const bf16x8*>(&Vh[(size_t)((k0) + sr) * LDK + sc]); \
;     st_[i].ks = *reinterpret_cast<const bf16x8*>(&Kh[(size_t)((k0) + sr) * LDK + sc]); \
;     if (DQ == 96) st_[i].kr = *reinterpret_cast<const bf16x8*>(&Kr[(size_t)((k0) + sr2) * 32 + sc2]); } while (0)
; #define SWRITE(b, i) do { *(bf16x8*)(V_lds + (b) * SHM_V + vst0) = st_[i].vs; *(bf16x8*)(K_lds + (b) * SHM_K + kst0) = st_[i].ks; \
;     if (DQ == 96) { if (tid < 256) *(bf16x8*)(K_lds + (b) * SHM_K + kst2) = st_[i].kr; } } while (0)
; template <int DQ, bool WIN, int LDQ, int LDK> ...
;     ...
;     const int tid = otid(), wid = __builtin_amdgcn_readfirstlane(tid >> 6), lane = tid & 63, r32 = lane & 31, hi = lane >> 5;
;     char* V_lds = lds; char* K_lds = lds + 2 * SHM_V;
;     float* wsf = (float*)(lds + 2 * SHM_V + 2 * SHM_K) + wid * 64; float* li_l = wsf; float* al_l = wsf + 32;
;     float m_reg = -1e30f, l_reg = 0; f32x16 o[2] = {}; bf16x8 qr[ND];
;     const bf16_t* Qw = Qb + (size_t)(wid * 32 + r32) * LDQ + hi * 8;
; #pragma unroll
;     for (int d0 = 0; d0 < ND; ++d0) qr[d0] = *reinterpret_cast<const bf16x8*>(Qw + d0 * 16);
;     const int sr = tid >> 3, sc = (tid & 7) * 8, vst0 = v_st(sr, sc);
;     const int kst0 = sr * KROW + sc * 2;
;     const int sr2 = (tid & 255) >> 2, sc2 = (tid & 3) * 8; const int kst2 = sr2 * KROW + 128 + sc2 * 2;
;     const int vb0 = (int)(uintptr_t)V_lds + v_rd_base(lane);
;     const int qrow = q0 + wid * 32 + r32;
;     struct { bf16x8 vs, ks, kr; } st_[2];
;     ...
;     f32x16 pA0, pA1, pB0, pB1; float mnA, mnB, alA, alB; bf16x8 pa0, pa1, pa2, pa3;
;     constexpr int SE = 0, SO = 1;
;     SLOAD(SE, KBASE(0)); asm volatile("s_waitcnt vmcnt(0)" ::: "memory"); SWRITE(0, SE); __syncthreads();
	v_mov_b32_e32 v99, v181
	s_mov_b32 s37, s36
	v_ashrrev_i32_e32 v114, 3, v99
	v_lshlrev_b32_e32 v12, 3, v99
	v_and_b32_e32 v64, 56, v12
	v_mad_i64_i32 v[2:3], s[0:1], v114, s83, 0
	v_or_b32_e32 v2, v2, v64
	v_lshl_add_u64 v[6:7], v[2:3], 1, s[4:5]
	global_load_dwordx4 v[2:5], v[6:7], off offset:1280
	s_nop 0
	global_load_dwordx4 v[6:9], v[6:7], off offset:1024
	v_readfirstlane_b32 s1, v99
	s_ashr_i32 s0, s1, 1
	v_mov_b32_e32 v10, s0
	v_bfe_u32 v1, v99, 5, 1
	v_bfi_b32 v13, s79, v10, v99
	v_mov_b64_e32 v[10:11], s[6:7]
	v_mad_i64_i32 v[10:11], s[6:7], v13, s78, v[10:11]
	v_lshlrev_b32_e32 v146, 4, v1
	v_lshl_add_u64 v[10:11], v[10:11], 0, v[146:147]
	global_load_dwordx4 v[78:81], v[10:11], off
	global_load_dwordx4 v[74:77], v[10:11], off offset:32
	global_load_dwordx4 v[70:73], v[10:11], off offset:64
	global_load_dwordx4 v[66:69], v[10:11], off offset:96
	v_and_b32_e32 v116, 31, v99
	v_and_b32_e32 v13, 0x1fffff0, v114
	v_lshlrev_b32_e32 v14, 1, v114
	v_lshrrev_b32_e32 v15, 1, v114
	v_and_b32_e32 v10, 3, v114
	v_mad_u32_u24 v11, v116, s82, 0
	v_and_or_b32 v13, v14, 8, v13
	v_and_or_b32 v14, v15, 4, v10
	v_lshlrev_b32_e32 v10, 1, v64
	v_bfe_u32 v12, v12, 5, 1
	v_add_u32_e32 v120, v11, v146
	v_lshrrev_b32_e32 v13, 2, v13
	v_and_b32_e32 v15, 48, v10
	v_mad_u64_u32 v[10:11], s[6:7], v114, s82, v[10:11]
	v_or_b32_e32 v11, v13, v12
	v_lshl_or_b32 v12, v14, 6, v15
	v_add_u32_e32 v122, 0, v10
	v_lshl_or_b32 v10, v11, 9, v12
	v_add_u32_e32 v123, 0, v10
	s_waitcnt vmcnt(0)
	v_lshlrev_b32_e32 v58, 4, v99
	v_lshlrev_b32_e32 v59, 1, v99
	v_and_b32_e32 v63, 0xc0, v58
	v_and_b32_e32 v65, 32, v59
	v_and_b32_e32 v115, 63, v99
	v_lshlrev_b32_e32 v62, 3, v115
	v_add_u32_e32 v82, 64, v114
	v_add_u32_e32 v83, 0x80, v114
	v_and_or_b32 v84, v62, 24, v63
	v_and_b32_e32 v85, 0x100, v62
	v_mad_i64_i32 v[62:63], s[6:7], v82, s83, 0
	v_or_b32_e32 v62, v62, v64
	v_lshl_add_u64 v[62:63], v[62:63], 1, s[4:5]
	v_or3_b32 v118, v84, v65, v85
	s_and_b32 s1, s1, 0x3fffffc0
	s_lshl_b32 s1, s1, 2
	s_andn2_b32 s0, s0, 31
	s_add_i32 s1, s1, 0
	s_cmp_lg_u32 0, -1
	s_mov_b32 s38, s36
	s_mov_b32 s39, s36
	s_mov_b32 s40, s36
	s_mov_b32 s41, s36
	s_mov_b32 s42, s36
	s_mov_b32 s43, s36
	s_mov_b32 s44, s36
	s_mov_b32 s45, s36
	s_mov_b32 s46, s36
	s_mov_b32 s47, s36
	s_mov_b32 s48, s36
	s_mov_b32 s49, s36
	s_mov_b32 s50, s36
	s_mov_b32 s51, s36
	s_mov_b32 s22, -1
	v_lshl_add_u32 v117, v116, 2, s1
	s_waitcnt vmcnt(5)
	ds_write_b128 v123, v[2:5]
	s_waitcnt vmcnt(4)
	ds_write_b128 v122, v[6:9] offset:16384
	s_waitcnt lgkmcnt(0)
	s_barrier
; __device__ __forceinline__ int crow(int r, int hi) { return (r & 3) + 8 * (r >> 2) + 4 * hi; }
; #define SLOAD(i, k0) do { st_[i].vs = *reinterpret_cast<const bf16x8*>(&Vh[(size_t)((k0) + sr) * LDK + sc]); \
;     st_[i].ks = *reinterpret_cast<const bf16x8*>(&Kh[(size_t)((k0) + sr) * LDK + sc]); \
;     if (DQ == 96) st_[i].kr = *reinterpret_cast<const bf16x8*>(&Kr[(size_t)((k0) + sr2) * 32 + sc2]); } while (0)
; #define SWRITE(b, i) do { *(bf16x8*)(V_lds + (b) * SHM_V + vst0) = st_[i].vs; *(bf16x8*)(K_lds + (b) * SHM_K + kst0) = st_[i].ks; \
;     if (DQ == 96) { if (tid < 256) *(bf16x8*)(K_lds + (b) * SHM_K + kst2) = st_[i].kr; } } while (0)
; template <int DQ, bool WIN>
; __device__ __forceinline__ void partialSM_s(f32x16& p0, f32x16& p1, float& m_reg, float& mn, float& alpha, int dlt, int hi) {
;     constexpr float C = 1.0f, SCALE = 1.0f / 1.4426950408889634f;
;     if (WIN) {
; #pragma unroll
;         for (int r = 0; r < 16; ++r) { const int d0 = dlt - crow(r, hi), d1 = d0 - 32;
;             if (d0 > 128 || d0 < -128) p0[r] = -INFINITY;
;             if (d1 > 128 || d1 < -128) p1[r] = -INFINITY; }
;     }
;     float pmax = p0[0];
; #pragma unroll
;     for (int r = 1; r < 16; ++r) pmax = fmaxf(pmax, p0[r]);
; #pragma unroll
;     for (int r = 0; r < 16; ++r) pmax = fmaxf(pmax, p1[r]);
;     { auto rr = __builtin_amdgcn_permlane32_swap(__float_as_uint(pmax), __float_as_uint(pmax), false, false);
;       pmax = fmaxf(__uint_as_float(rr[0]), __uint_as_float(rr[1])); }
;     if (__builtin_expect(__all(pmax - m_reg <= ATT_THR / SCALE), 1)) { mn = m_reg; alpha = 1.f; }
;     else { mn = fmaxf(m_reg, pmax); alpha = __builtin_amdgcn_exp2f((m_reg - mn) * C); m_reg = mn; }
;     const float mnC = -mn * C;
; #pragma unroll
;     for (int r = 0; r < 16; ++r) p0[r] = fmaf(p0[r], C, mnC);
; #pragma unroll
;     for (int r = 0; r < 16; ++r) p1[r] = fmaf(p1[r], C, mnC);
; #pragma unroll
;     for (int r = 0; r < 16; ++r) p0[r] = __builtin_amdgcn_exp2f(p0[r]);
; }
; template <int DQ, bool WIN, int LDQ, int LDK> ...
;     ...
;     qkt_s<DQ>(pA0, pA1, K_lds, qr, r32, hi); partialSM_s<DQ, WIN>(pA0, pA1, m_reg, mnA, alA, qrow - KBASE(0), hi);
;     SLOAD(SO, KBASE(1)); if (2 < NT) SLOAD(SE, KBASE(2));
;     SWAIT(); SWRITE(1, SO); __syncthreads();
	ds_read_b128 v[2:5], v120 offset:16384
	s_waitcnt vmcnt(3) lgkmcnt(0)
	v_mfma_f32_32x32x16_bf16 v[34:49], v[2:5], v[78:81], 0
	ds_read_b128 v[6:9], v120 offset:20992
	ds_read_b128 v[10:13], v120 offset:16416
	ds_read_b128 v[50:53], v120 offset:21024
	ds_read_b128 v[54:57], v120 offset:16448
	s_waitcnt lgkmcnt(3)
	v_mfma_f32_32x32x16_bf16 v[18:33], v[6:9], v[78:81], 0
	s_waitcnt vmcnt(2) lgkmcnt(2)
	v_mfma_f32_32x32x16_bf16 v[34:49], v[10:13], v[74:77], v[34:49]
	v_mov_b64_e32 v[2:3], s[36:37]
	v_mov_b64_e32 v[16:17], s[50:51]
	v_mov_b64_e32 v[4:5], s[38:39]
	v_mov_b64_e32 v[6:7], s[40:41]
	v_mov_b64_e32 v[8:9], s[42:43]
	v_mov_b64_e32 v[10:11], s[44:45]
	v_mov_b64_e32 v[12:13], s[46:47]
	s_waitcnt lgkmcnt(1)
	v_mfma_f32_32x32x16_bf16 v[18:33], v[50:53], v[74:77], v[18:33]
	ds_read_b128 v[50:53], v120 offset:21056
	ds_read_b128 v[58:61], v120 offset:16480
	v_mov_b64_e32 v[14:15], s[48:49]
	s_waitcnt vmcnt(1) lgkmcnt(2)
	v_mfma_f32_32x32x16_bf16 v[34:49], v[54:57], v[70:73], v[34:49]
	ds_read_b128 v[54:57], v120 offset:21088
	s_waitcnt lgkmcnt(2)
	v_mfma_f32_32x32x16_bf16 v[18:33], v[50:53], v[70:73], v[18:33]
	v_mad_i64_i32 v[50:51], s[6:7], v83, s83, 0
	v_or_b32_e32 v50, v50, v64
	v_lshl_add_u64 v[64:65], v[50:51], 1, s[4:5]
	s_cselect_b32 s6, 0, 0
	v_add_u32_e32 v121, s6, v118
	v_cmp_gt_u32_e64 s[4:5], 32, v115
	s_waitcnt vmcnt(0) lgkmcnt(1)
	v_mfma_f32_32x32x16_bf16 v[34:49], v[58:61], v[66:69], v[34:49]
	global_load_dwordx4 v[50:53], v[62:63], off offset:1280
	global_load_dwordx4 v[58:61], v[62:63], off offset:1024
	global_load_dwordx4 v[86:89], v[64:65], off offset:1024
	global_load_dwordx4 v[82:85], v[64:65], off offset:1280
	s_waitcnt vmcnt(2)
	s_waitcnt vmcnt(3)
	ds_write_b128 v123, v[50:53] offset:8192
	s_waitcnt vmcnt(2)
	ds_write_b128 v122, v[58:61] offset:25600
	s_waitcnt lgkmcnt(2)
	v_mfma_f32_32x32x16_bf16 v[18:33], v[54:57], v[66:69], v[18:33]
	s_nop 1
	v_max_f32_e32 v54, v35, v35
	v_max_f32_e32 v55, v34, v34
	v_max_f32_e32 v54, v55, v54
	v_max3_f32 v54, v54, v36, v37
	v_max3_f32 v54, v54, v38, v39
	v_max3_f32 v54, v54, v40, v41
	v_max3_f32 v54, v54, v42, v43
	v_max3_f32 v54, v54, v44, v45
	v_max3_f32 v54, v54, v46, v47
	v_max3_f32 v54, v54, v48, v49
	v_max3_f32 v54, v54, v18, v19
	v_max3_f32 v54, v54, v20, v21
	v_max3_f32 v54, v54, v22, v23
	v_max3_f32 v54, v54, v24, v25
	v_max3_f32 v54, v54, v26, v27
	v_max3_f32 v54, v54, v28, v29
	v_max3_f32 v54, v54, v30, v31
	v_max3_f32 v54, v54, v32, v33
	v_mov_b32_e32 v55, v54
	s_nop 1
	v_permlane32_swap_b32_e32 v54, v55
	v_max_f32_e32 v55, v55, v55
	v_max_f32_e32 v54, v54, v54
	v_max_f32_e32 v54, v54, v55
	v_add_f32_e32 v55, 0x7149f2ca, v54
	v_cmp_ge_f32_e32 vcc, s89, v55
	s_cmp_eq_u64 vcc, exec
	s_cselect_b64 vcc, -1, 0
	s_addk_i32 s6, 0x2000
	v_max_f32_e32 v54, 0xf149f2ca, v54
	v_add_u32_e32 v119, s6, v118
	s_add_u32 s6, s33, s67
	v_sub_f32_e32 v55, 0xf149f2ca, v54
	v_cndmask_b32_e32 v98, v54, v154, vcc
	s_addc_u32 s7, 0, 0
	v_exp_f32_e32 v55, v55
	v_sub_f32_e32 v54, v34, v98
	v_sub_f32_e32 v56, v35, v98
	v_sub_f32_e32 v57, v36, v98
	v_sub_f32_e32 v62, v37, v98
	v_sub_f32_e32 v38, v38, v98
	v_sub_f32_e32 v39, v39, v98
	v_sub_f32_e32 v40, v40, v98
	v_sub_f32_e32 v41, v41, v98
	v_sub_f32_e32 v42, v42, v98
	v_sub_f32_e32 v43, v43, v98
	v_sub_f32_e32 v44, v44, v98
	v_sub_f32_e32 v45, v45, v98
	v_sub_f32_e32 v46, v46, v98
	v_sub_f32_e32 v47, v47, v98
	v_sub_f32_e32 v48, v48, v98
	v_sub_f32_e32 v49, v49, v98
	v_sub_f32_e32 v34, v18, v98
	v_sub_f32_e32 v35, v19, v98
	v_sub_f32_e32 v36, v20, v98
	v_mov_b64_e32 v[18:19], s[6:7]
	v_and_b32_e32 v20, 7, v99
	v_sub_f32_e32 v37, v21, v98
	v_exp_f32_e32 v131, v54
	v_exp_f32_e32 v133, v56
	v_exp_f32_e32 v129, v57
	v_exp_f32_e32 v132, v62
	v_exp_f32_e32 v113, v38
	v_exp_f32_e32 v130, v39
	v_exp_f32_e32 v112, v40
	v_exp_f32_e32 v128, v41
	v_exp_f32_e32 v109, v42
	v_exp_f32_e32 v111, v43
	v_exp_f32_e32 v107, v44
	v_exp_f32_e32 v110, v45
	v_exp_f32_e32 v105, v46
	v_exp_f32_e32 v108, v47
	v_exp_f32_e32 v104, v48
	v_exp_f32_e32 v106, v49
	v_mad_i64_i32 v[18:19], s[6:7], v114, s78, v[18:19]
	v_lshlrev_b32_e32 v20, 4, v20
	v_mov_b32_e32 v21, v147
	v_lshl_add_u64 v[18:19], v[18:19], 0, v[20:21]
	v_sub_f32_e32 v90, v22, v98
	v_sub_f32_e32 v91, v23, v98
	v_sub_f32_e32 v92, v24, v98
	v_sub_f32_e32 v93, v25, v98
	v_sub_f32_e32 v94, v26, v98
	v_sub_f32_e32 v95, v27, v98
	v_sub_f32_e32 v102, v28, v98
	v_sub_f32_e32 v103, v29, v98
	v_sub_f32_e32 v96, v30, v98
	v_sub_f32_e32 v97, v31, v98
	v_sub_f32_e32 v100, v32, v98
	v_sub_f32_e32 v101, v33, v98
	v_lshl_add_u64 v[114:115], s[16:17], 0, v[18:19]
	v_mov_b64_e32 v[32:33], v[16:17]
	v_cndmask_b32_e64 v124, v55, 1.0, vcc
	v_mov_b32_e32 v118, 0
	v_mov_b64_e32 v[30:31], v[14:15]
	v_mov_b64_e32 v[28:29], v[12:13]
	v_mov_b64_e32 v[26:27], v[10:11]
	v_mov_b64_e32 v[24:25], v[8:9]
	v_mov_b64_e32 v[22:23], v[6:7]
	v_mov_b64_e32 v[20:21], v[4:5]
	v_mov_b64_e32 v[18:19], v[2:3]
	s_waitcnt lgkmcnt(0)
	s_barrier

; __device__ __forceinline__ int otid() { int t = threadIdx.x; asm volatile("" : "+v"(t)); return t; }
; template <int DQ, bool WIN, int LDQ, int LDK> ...
;     ...
;     const int tid = otid(), wid = __builtin_amdgcn_readfirstlane(tid >> 6), lane = tid & 63, r32 = lane & 31, hi = lane >> 5;
;     char* V_lds = lds; char* K_lds = lds + 2 * SHM_V;
;     float* wsf = (float*)(lds + 2 * SHM_V + 2 * SHM_K) + wid * 64; float* li_l = wsf;
;     volatile int* redo_flag = (volatile int*)(lds + 2 * SHM_V + 2 * SHM_K + 8 * 64 * 4);
;     if (tid == 0) *redo_flag = 0;
.LBB0_1084:
	v_mov_b32_e32 v80, v181
	s_nop 0
	v_readfirstlane_b32 s4, v80
	v_cmp_eq_u32_e32 vcc, 0, v80
	s_and_saveexec_b64 s[0:1], vcc
	s_cbranch_execz .LBB0_1086
	s_add_i32 s5, 0, 0xb000
	s_mov_b64 s[6:7], src_shared_base
	s_cmp_lg_u32 s5, -1
	s_cselect_b32 s5, s5, 0
	s_cselect_b32 s6, s7, 0
	v_mov_b32_e32 v0, s5
	v_mov_b32_e32 v1, s6
	ds_write_b32 v0, v113

; __device__ __forceinline__ unsigned cvtpk(float lo, float hi) { unsigned r; asm volatile("v_cvt_pk_bf16_f32 %0, %1, %2" : "=v"(r) : "v"(lo), "v"(hi)); return r; }
; __device__ __forceinline__ int crow(int r, int hi) { return (r & 3) + 8 * (r >> 2) + 4 * hi; }
; template <int DQ, bool WIN, int LDQ, int LDK> ...
;     ...
;     float rli[16]; bool fin = true;
; #pragma unroll
;     for (int r = 0; r < 16; ++r) { fin = fin && (lsum[r] < ATT_GUARD) && (lsum[r] > 0.f); rli[r] = __builtin_amdgcn_rcpf(lsum[r]); }
;     if (!__all(fin)) { if (lane == 0) *redo_flag = 1; }
;     bf16_t* Ow = Ob + (size_t)(wid * 32) * LDO;
; #pragma unroll
;     for (int r = 0; r < 16; ++r) { const int orow = crow(r, hi);
; #pragma unroll
;         for (int d0 = 0; d0 < 2; ++d0) Ow[(size_t)orow * LDO + d0 * 32 + r32] = (bf16_t)(cvtpk(o[d0][r] * rli[r], 0.f) & 0xffffu); }
;     __syncthreads();
;     const int redo = __builtin_amdgcn_readfirstlane(*redo_flag);
.LBB0_1102:
	s_or_b64 exec, exec, s[4:5]
	s_lshl_b64 s[4:5], s[14:15], 11
	s_add_u32 s4, s46, s4
	s_addc_u32 s5, s47, s5
	s_lshl_b32 s14, s22, 7
	s_add_u32 s14, s4, s14
	s_addc_u32 s15, s5, 0
	v_rcp_f32_e32 v51, v32
	s_ashr_i32 s17, s16, 31
	s_lshl_b64 s[4:5], s[16:17], 11
	s_add_u32 s4, s14, s4
	s_addc_u32 s5, s15, s5
	v_lshlrev_b32_e32 v112, 1, v188
	v_rcp_f32_e32 v48, v35
	v_rcp_f32_e32 v49, v34
	v_rcp_f32_e32 v50, v33
	v_lshlrev_b32_e32 v32, 13, v187
	v_lshl_add_u64 v[34:35], s[4:5], 0, v[112:113]
	v_mov_b32_e32 v33, v113
	v_mul_f32_e32 v0, v0, v51
	v_lshl_add_u64 v[32:33], v[34:35], 0, v[32:33]
	v_cvt_pk_bf16_f32 v0, v0, v113
	global_store_short v[32:33], v0, off
	v_mul_f32_e32 v0, v16, v51
	v_cvt_pk_bf16_f32 v0, v0, v113
	global_store_short v[32:33], v0, off offset:64
	v_mul_f32_e32 v0, v1, v50
	v_cvt_pk_bf16_f32 v0, v0, v113
	global_store_short v[32:33], v0, off offset:2048
	v_mul_f32_e32 v0, v17, v50
	v_cvt_pk_bf16_f32 v0, v0, v113
	global_store_short v[32:33], v0, off offset:2112
	v_mul_f32_e32 v0, v2, v49
	s_movk_i32 s4, 0x1000
	v_cvt_pk_bf16_f32 v2, v0, v113
	v_add_co_u32_e32 v0, vcc, s4, v32
	v_rcp_f32_e32 v36, v36
	s_nop 0
	v_addc_co_u32_e32 v1, vcc, 0, v33, vcc
	global_store_short v[0:1], v2, off
	v_mul_f32_e32 v2, v18, v49
	v_cvt_pk_bf16_f32 v2, v2, v113
	global_store_short v[0:1], v2, off offset:64
	v_mul_f32_e32 v2, v3, v48
	v_cvt_pk_bf16_f32 v2, v2, v113
	global_store_short v[0:1], v2, off offset:2048
	v_mul_f32_e32 v2, v19, v48
	v_cvt_pk_bf16_f32 v2, v2, v113
	global_store_short v[0:1], v2, off offset:2112
	v_mul_f32_e32 v0, v4, v36
	s_movk_i32 s4, 0x4000
	v_cvt_pk_bf16_f32 v4, v0, v113
	v_add_co_u32_e32 v0, vcc, s4, v32
	s_movk_i32 s4, 0x5000
	s_nop 0
	v_addc_co_u32_e32 v1, vcc, 0, v33, vcc
	v_rcp_f32_e32 v37, v37
	v_add_co_u32_e32 v2, vcc, s4, v32
	v_rcp_f32_e32 v38, v38
	s_nop 0
	v_addc_co_u32_e32 v3, vcc, 0, v33, vcc
	global_store_short v[2:3], v4, off offset:-4096
	v_mul_f32_e32 v4, v20, v36
	v_cvt_pk_bf16_f32 v4, v4, v113
	global_store_short v[0:1], v4, off offset:64
	v_mul_f32_e32 v4, v5, v37
	v_cvt_pk_bf16_f32 v4, v4, v113
	global_store_short v[0:1], v4, off offset:2048
	v_mul_f32_e32 v4, v21, v37
	v_rcp_f32_e32 v39, v39
	v_cvt_pk_bf16_f32 v4, v4, v113
	global_store_short v[0:1], v4, off offset:2112
	v_mul_f32_e32 v0, v6, v38
	v_cvt_pk_bf16_f32 v0, v0, v113
	global_store_short v[2:3], v0, off
	v_mul_f32_e32 v0, v22, v38
	v_cvt_pk_bf16_f32 v0, v0, v113
	v_rcp_f32_e32 v40, v40
	global_store_short v[2:3], v0, off offset:64
	v_mul_f32_e32 v0, v7, v39
	v_cvt_pk_bf16_f32 v0, v0, v113
	global_store_short v[2:3], v0, off offset:2048
	v_mul_f32_e32 v0, v23, v39
	v_cvt_pk_bf16_f32 v0, v0, v113
	global_store_short v[2:3], v0, off offset:2112
	v_mul_f32_e32 v0, v8, v40
	s_mov_b32 s4, 0x8000
	v_cvt_pk_bf16_f32 v4, v0, v113
	v_add_co_u32_e32 v0, vcc, s4, v32
	s_mov_b32 s4, 0x9000
	s_nop 0
	v_addc_co_u32_e32 v1, vcc, 0, v33, vcc
	v_rcp_f32_e32 v41, v41
	v_add_co_u32_e32 v2, vcc, s4, v32
	v_rcp_f32_e32 v42, v42
	s_nop 0
	v_addc_co_u32_e32 v3, vcc, 0, v33, vcc
	global_store_short v[2:3], v4, off offset:-4096
	v_mul_f32_e32 v4, v24, v40
	v_cvt_pk_bf16_f32 v4, v4, v113
	global_store_short v[0:1], v4, off offset:64
	v_mul_f32_e32 v4, v9, v41
	v_cvt_pk_bf16_f32 v4, v4, v113
	global_store_short v[0:1], v4, off offset:2048
	v_mul_f32_e32 v4, v25, v41
	v_rcp_f32_e32 v43, v43
	v_cvt_pk_bf16_f32 v4, v4, v113
	global_store_short v[0:1], v4, off offset:2112
	v_mul_f32_e32 v0, v10, v42
	v_cvt_pk_bf16_f32 v0, v0, v113
	global_store_short v[2:3], v0, off
	v_mul_f32_e32 v0, v26, v42
	v_cvt_pk_bf16_f32 v0, v0, v113
	v_rcp_f32_e32 v44, v44
	global_store_short v[2:3], v0, off offset:64
	v_mul_f32_e32 v0, v11, v43
	v_cvt_pk_bf16_f32 v0, v0, v113
	global_store_short v[2:3], v0, off offset:2048
	v_mul_f32_e32 v0, v27, v43
	v_cvt_pk_bf16_f32 v0, v0, v113
	global_store_short v[2:3], v0, off offset:2112
	v_mul_f32_e32 v0, v12, v44
	s_mov_b32 s4, 0xc000
	v_cvt_pk_bf16_f32 v4, v0, v113
	v_add_co_u32_e32 v0, vcc, s4, v32
	s_mov_b32 s4, 0xd000
	s_nop 0
	v_addc_co_u32_e32 v1, vcc, 0, v33, vcc
	v_rcp_f32_e32 v45, v45
	v_add_co_u32_e32 v2, vcc, s4, v32
	v_rcp_f32_e32 v46, v46
	s_nop 0
	v_addc_co_u32_e32 v3, vcc, 0, v33, vcc
	global_store_short v[2:3], v4, off offset:-4096
	v_mul_f32_e32 v4, v28, v44
	v_cvt_pk_bf16_f32 v4, v4, v113
	global_store_short v[0:1], v4, off offset:64
	v_mul_f32_e32 v4, v13, v45
	v_cvt_pk_bf16_f32 v4, v4, v113
	global_store_short v[0:1], v4, off offset:2048
	v_mul_f32_e32 v4, v29, v45
	v_rcp_f32_e32 v47, v47
	v_cvt_pk_bf16_f32 v4, v4, v113
	global_store_short v[0:1], v4, off offset:2112
	v_mul_f32_e32 v0, v14, v46
	v_cvt_pk_bf16_f32 v0, v0, v113
	global_store_short v[2:3], v0, off
	v_mul_f32_e32 v0, v30, v46
	v_cvt_pk_bf16_f32 v0, v0, v113
	global_store_short v[2:3], v0, off offset:64
	v_mul_f32_e32 v0, v15, v47
	s_add_i32 s4, 0, 0xb000
	v_cvt_pk_bf16_f32 v0, v0, v113
	s_cmp_lg_u32 s4, -1
	global_store_short v[2:3], v0, off offset:2048
	v_mul_f32_e32 v0, v31, v47
	s_cselect_b32 s16, s4, 0
	s_mov_b64 s[4:5], src_shared_base
	v_cvt_pk_bf16_f32 v0, v0, v113
	s_cselect_b32 s4, s5, 0
	global_store_short v[2:3], v0, off offset:2112
	v_mov_b32_e32 v0, s16
	v_mov_b32_e32 v1, s4
	s_waitcnt lgkmcnt(0)
	s_barrier
; __device__ __forceinline__ int otid() { int t = threadIdx.x; asm volatile("" : "+v"(t)); return t; }
; __device__ __forceinline__ int v_st(int k, int c) { const int kk = (k & ~0xC) | ((k & 4) << 1) | ((k & 8) >> 1); return ((kk >> 3) * 2 + (c >> 5)) * 512 + ((kk & 7) * 32 + (c & 31)) * 2; }
; __device__ __forceinline__ int v_rd_base(int lane) { return ((lane & 3) << 3) | (((lane >> 2) & 3) << 6) | (((lane >> 4) & 1) << 5) | (((lane >> 5) & 1) << 8); }
; template <int DQ, bool WIN, int LDQ, int LDK> ...
;     ...
;     const int tid = otid(), wid = __builtin_amdgcn_readfirstlane(tid >> 6), lane = tid & 63, r32 = lane & 31, hi = lane >> 5;
;     char* V_lds = lds; char* K_lds = lds + 2 * SHM_V;
;     float* wsf = (float*)(lds + 2 * SHM_V + 2 * SHM_K) + wid * 64; float* li_l = wsf; float* al_l = wsf + 32;
;     float m_reg = -1e30f, l_reg = 0; f32x16 o[2] = {}; bf16x8 qr[ND];
;     const bf16_t* Qw = Qb + (size_t)(wid * 32 + r32) * LDQ + hi * 8;
; #pragma unroll
;     for (int d0 = 0; d0 < ND; ++d0) qr[d0] = *reinterpret_cast<const bf16x8*>(Qw + d0 * 16);
;     const int sr = tid >> 3, sc = (tid & 7) * 8, vst0 = v_st(sr, sc);
;     const int kst0 = sr * KROW + sc * 2;
;     const int sr2 = (tid & 255) >> 2, sc2 = (tid & 3) * 8; const int kst2 = sr2 * KROW + 128 + sc2 * 2;
;     const int vb0 = (int)(uintptr_t)V_lds + v_rd_base(lane);
;     const int qrow = q0 + wid * 32 + r32;
;     struct { bf16x8 vs, ks, kr; } st_[2];
; template <int DQ, bool WIN, int LDQ, int LDK> ...
;     ...
;     const int redo = __builtin_amdgcn_readfirstlane(*redo_flag);
;     __syncthreads();
;     return redo;
	ds_read_b32 v0, v0
	s_waitcnt lgkmcnt(0)
	s_barrier
	v_readfirstlane_b32 s4, v0
	s_cmp_eq_u32 s4, 0
	s_cbranch_scc1 .LBB0_1083
	v_mov_b32_e32 v36, v181
	s_movk_i32 s4, 0xffe0
	v_readfirstlane_b32 s16, v36
	s_ashr_i32 s17, s16, 1
	v_mov_b32_e32 v0, s17
	v_bfe_u32 v138, v36, 5, 1
	v_bfi_b32 v2, s4, v0, v36
	v_mov_b64_e32 v[0:1], s[12:13]
	s_movk_i32 s4, 0xc00
	v_mad_i64_i32 v[0:1], s[4:5], v2, s4, v[0:1]
	v_lshlrev_b32_e32 v112, 4, v138
	v_lshl_add_u64 v[0:1], v[0:1], 0, v[112:113]
	global_load_dwordx4 v[84:87], v[0:1], off
	global_load_dwordx4 v[80:83], v[0:1], off offset:32
	global_load_dwordx4 v[76:79], v[0:1], off offset:64
	global_load_dwordx4 v[72:75], v[0:1], off offset:96
	global_load_dwordx4 v[68:71], v[0:1], off offset:128
	global_load_dwordx4 v[64:67], v[0:1], off offset:160
	v_ashrrev_i32_e32 v0, 3, v36
	v_and_b32_e32 v2, 0x1fffff0, v0
	v_lshlrev_b32_e32 v3, 1, v0
	v_lshlrev_b32_e32 v1, 3, v36
	v_and_or_b32 v2, v3, 8, v2
	v_lshrrev_b32_e32 v2, 2, v2
	v_bfe_u32 v4, v1, 5, 1
	v_and_b32_e32 v41, 56, v1
	v_lshrrev_b32_e32 v3, 1, v0
	v_or_b32_e32 v4, v2, v4
	v_and_b32_e32 v2, 3, v0
	v_and_or_b32 v3, v3, 4, v2
	v_lshlrev_b32_e32 v2, 1, v41
	v_and_b32_e32 v5, 48, v2
	v_and_b32_e32 v37, 24, v1
	v_ashrrev_i32_e32 v1, 31, v0
	v_lshl_or_b32 v3, v3, 6, v5
	s_movk_i32 s4, 0xd0
	v_lshlrev_b64 v[32:33], 12, v[0:1]
	v_mad_u64_u32 v[8:9], s[4:5], v0, s4, v[2:3]
	v_or_b32_e32 v0, v32, v2
	v_mov_b32_e32 v1, v33
	v_lshl_or_b32 v12, v4, 9, v3
	v_lshl_add_u64 v[4:5], s[6:7], 0, v[0:1]
	global_load_dwordx4 v[0:3], v[4:5], off offset:128
	s_nop 0
	global_load_dwordx4 v[4:7], v[4:5], off
	v_bfe_u32 v9, v36, 2, 6
	v_lshlrev_b32_e32 v38, 5, v9
	v_mul_u32_u24_e32 v39, 0xd0, v9
	v_or_b32_e32 v9, v38, v37
	s_waitcnt vmcnt(0)
	s_movk_i32 s4, 0xff
	v_lshlrev_b32_e32 v10, 1, v9
	v_mov_b32_e32 v11, v113
	v_cmp_lt_i32_e64 s[40:41], s4, v36
	s_movk_i32 s4, 0x100
	v_lshlrev_b32_e32 v40, 1, v37
	v_lshl_add_u64 v[34:35], s[8:9], 0, v[10:11]
	v_add_u32_e32 v143, 0, v12
	v_add_u32_e32 v144, 0, v8
	v_cmp_gt_i32_e64 s[42:43], s4, v36
	s_waitcnt vmcnt(1)
	ds_write_b128 v143, v[0:3]
	s_waitcnt vmcnt(0)
	ds_write_b128 v144, v[4:7] offset:16384
	s_and_saveexec_b64 s[4:5], s[42:43]
	s_cbranch_execz .LBB0_1105
	global_load_dwordx4 v[0:3], v[34:35], off
	v_add3_u32 v4, v39, v40, 0
	s_waitcnt vmcnt(0)
	ds_write_b128 v4, v[0:3] offset:16512
